# residual GEMM epilogue: all 32 H loads issued before the single wait instead of load-wait-store per piece
# speedup vs baseline: 1.0275x; 1.0004x over previous
; __device__ __forceinline__ unsigned cvt_pk_bf16(float lo, float hi) { unsigned r; asm volatile("v_cvt_pk_bf16_f32 %0, %1, %2" : "=v"(r) : "v"(lo), "v"(hi)); return r; }
; __device__ __forceinline__ float ebflo(unsigned w) { return __uint_as_float(w << 16); }
; __device__ __forceinline__ float ebfhi(unsigned w) { return __uint_as_float(w & 0xffff0000u); }
;     __device__ __forceinline__ void operator()(const f32x4 (&acc)[2][2][4][2], const Unit& u, int wr, int wc, int fr, int fq) const {
;         const int row0 = u.pm * BM + wr * 64 + fr, col0 = u.pn * BM + wc * 32 + 4 * fq;
; #pragma unroll
;         for (int ai = 0; ai < 2; ++ai)
; #pragma unroll
;             for (int m = 0; m < 4; ++m) { bf16_t* rowp = H + (size_t)(row0 + ai * HALF + m * 16) * 1024 + col0;
; #pragma unroll
;                 for (int bj = 0; bj < 2; ++bj)
; #pragma unroll
;                     for (int n = 0; n < 2; ++n) { u32x2* q = (u32x2*)(rowp + bj * HALF + n * 16); const u32x2 hv = *q; const f32x4 a = acc[ai][bj][m][n];
;                         u32x2 w; w.x = cvt_pk_bf16(ebflo(hv.x) + a[0], ebfhi(hv.x) + a[1]); w.y = cvt_pk_bf16(ebflo(hv.y) + a[2], ebfhi(hv.y) + a[3]); *q = w; } }
;     }
.LBB0_650:
	s_andn2_b64 vcc, exec, s[10:11]
	s_cbranch_vccnz .LBB0_652
	v_lshl_or_b32 v146, s78, 8, v166
	v_ashrrev_i32_e32 v147, 31, v146
	v_lshlrev_b64 v[148:149], 11, v[144:145]
	v_lshl_add_u64 v[150:151], s[36:37], 0, v[148:149]
	v_lshlrev_b64 v[148:149], 1, v[146:147]
	v_lshl_add_u64 v[146:147], v[150:151], 0, v[148:149]
	global_load_dwordx2 v[190:191], v[146:147], off
	global_load_dwordx2 v[192:193], v[146:147], off offset:32
	global_load_dwordx2 v[194:195], v[146:147], off offset:256
	global_load_dwordx2 v[196:197], v[146:147], off offset:288
	s_mov_b64 s[10:11], 0x8000
	v_lshl_add_u64 v[148:149], v[146:147], 0, s[10:11]
	global_load_dwordx2 v[198:199], v[148:149], off
	global_load_dwordx2 v[200:201], v[148:149], off offset:32
	global_load_dwordx2 v[202:203], v[148:149], off offset:256
	global_load_dwordx2 v[204:205], v[148:149], off offset:288
	s_mov_b64 s[10:11], 0x10000
	v_lshl_add_u64 v[148:149], v[146:147], 0, s[10:11]
	global_load_dwordx2 v[206:207], v[148:149], off
	global_load_dwordx2 v[208:209], v[148:149], off offset:32
	global_load_dwordx2 v[210:211], v[148:149], off offset:256
	global_load_dwordx2 v[212:213], v[148:149], off offset:288
	s_mov_b64 s[10:11], 0x18000
	v_lshl_add_u64 v[148:149], v[146:147], 0, s[10:11]
	global_load_dwordx2 v[214:215], v[148:149], off
	global_load_dwordx2 v[216:217], v[148:149], off offset:32
	global_load_dwordx2 v[218:219], v[148:149], off offset:256
	global_load_dwordx2 v[220:221], v[148:149], off offset:288
	s_mov_b64 s[10:11], 0x40000
	v_lshl_add_u64 v[148:149], v[146:147], 0, s[10:11]
	global_load_dwordx2 v[222:223], v[148:149], off
	global_load_dwordx2 v[224:225], v[148:149], off offset:32
	global_load_dwordx2 v[226:227], v[148:149], off offset:256
	global_load_dwordx2 v[228:229], v[148:149], off offset:288
	s_mov_b64 s[10:11], 0x48000
	v_lshl_add_u64 v[148:149], v[146:147], 0, s[10:11]
	global_load_dwordx2 v[230:231], v[148:149], off
	global_load_dwordx2 v[232:233], v[148:149], off offset:32
	global_load_dwordx2 v[234:235], v[148:149], off offset:256
	global_load_dwordx2 v[236:237], v[148:149], off offset:288
	s_mov_b64 s[10:11], 0x50000
	v_lshl_add_u64 v[148:149], v[146:147], 0, s[10:11]
	global_load_dwordx2 v[238:239], v[148:149], off
	global_load_dwordx2 v[240:241], v[148:149], off offset:32
	global_load_dwordx2 v[242:243], v[148:149], off offset:256
	global_load_dwordx2 v[244:245], v[148:149], off offset:288
	s_mov_b64 s[10:11], 0x58000
	v_lshl_add_u64 v[148:149], v[146:147], 0, s[10:11]
	global_load_dwordx2 v[152:153], v[148:149], off
	global_load_dwordx2 v[154:155], v[148:149], off offset:32
	global_load_dwordx2 v[156:157], v[148:149], off offset:256
	global_load_dwordx2 v[158:159], v[148:149], off offset:288
	s_waitcnt vmcnt(0)
	v_lshlrev_b32_e32 v150, 16, v190
	v_and_b32_e32 v151, 0xffff0000, v190
	v_add_f32_e32 v150, v128, v150
	v_add_f32_e32 v151, v129, v151
	v_lshlrev_b32_e32 v160, 16, v191
	v_and_b32_e32 v161, 0xffff0000, v191
	v_cvt_pk_bf16_f32 v190, v150, v151
	v_add_f32_e32 v160, v130, v160
	v_add_f32_e32 v161, v131, v161
	s_nop 0
	v_cvt_pk_bf16_f32 v191, v160, v161
	s_nop 0
	global_store_dwordx2 v[146:147], v[190:191], off
	v_lshlrev_b32_e32 v150, 16, v192
	v_and_b32_e32 v151, 0xffff0000, v192
	v_add_f32_e32 v150, v124, v150
	v_add_f32_e32 v151, v125, v151
	v_lshlrev_b32_e32 v160, 16, v193
	v_and_b32_e32 v161, 0xffff0000, v193
	v_cvt_pk_bf16_f32 v192, v150, v151
	v_add_f32_e32 v160, v126, v160
	v_add_f32_e32 v161, v127, v161
	s_nop 0
	v_cvt_pk_bf16_f32 v193, v160, v161
	s_nop 0
	global_store_dwordx2 v[146:147], v[192:193], off offset:32
	v_lshlrev_b32_e32 v150, 16, v194
	v_and_b32_e32 v151, 0xffff0000, v194
	v_add_f32_e32 v150, v120, v150
	v_add_f32_e32 v151, v121, v151
	v_lshlrev_b32_e32 v160, 16, v195
	v_and_b32_e32 v161, 0xffff0000, v195
	v_cvt_pk_bf16_f32 v194, v150, v151
	v_add_f32_e32 v160, v122, v160
	v_add_f32_e32 v161, v123, v161
	s_nop 0
	v_cvt_pk_bf16_f32 v195, v160, v161
	s_nop 0
	global_store_dwordx2 v[146:147], v[194:195], off offset:256
	v_lshlrev_b32_e32 v150, 16, v196
	v_and_b32_e32 v151, 0xffff0000, v196
	v_add_f32_e32 v150, v116, v150
	v_add_f32_e32 v151, v117, v151
	v_lshlrev_b32_e32 v160, 16, v197
	v_and_b32_e32 v161, 0xffff0000, v197
	v_cvt_pk_bf16_f32 v196, v150, v151
	v_add_f32_e32 v160, v118, v160
	v_add_f32_e32 v161, v119, v161
	s_nop 0
	v_cvt_pk_bf16_f32 v197, v160, v161
	s_nop 0
	global_store_dwordx2 v[146:147], v[196:197], off offset:288
	s_mov_b64 s[10:11], 0x8000
	v_lshl_add_u64 v[148:149], v[146:147], 0, s[10:11]
	v_lshlrev_b32_e32 v150, 16, v198
	v_and_b32_e32 v151, 0xffff0000, v198
	v_add_f32_e32 v150, v112, v150
	v_add_f32_e32 v151, v113, v151
	v_lshlrev_b32_e32 v160, 16, v199
	v_and_b32_e32 v161, 0xffff0000, v199
	v_cvt_pk_bf16_f32 v198, v150, v151
	v_add_f32_e32 v160, v114, v160
	v_add_f32_e32 v161, v115, v161
	s_nop 0
	v_cvt_pk_bf16_f32 v199, v160, v161
	s_nop 0
	global_store_dwordx2 v[148:149], v[198:199], off
	v_lshlrev_b32_e32 v150, 16, v200
	v_and_b32_e32 v151, 0xffff0000, v200
	v_add_f32_e32 v150, v108, v150
	v_add_f32_e32 v151, v109, v151
	v_lshlrev_b32_e32 v160, 16, v201
	v_and_b32_e32 v161, 0xffff0000, v201
	v_cvt_pk_bf16_f32 v200, v150, v151
	v_add_f32_e32 v160, v110, v160
	v_add_f32_e32 v161, v111, v161
	s_nop 0
	v_cvt_pk_bf16_f32 v201, v160, v161
	s_nop 0
	global_store_dwordx2 v[148:149], v[200:201], off offset:32
	v_lshlrev_b32_e32 v150, 16, v202
	v_and_b32_e32 v151, 0xffff0000, v202
	v_add_f32_e32 v150, v104, v150
	v_add_f32_e32 v151, v105, v151
	v_lshlrev_b32_e32 v160, 16, v203
	v_and_b32_e32 v161, 0xffff0000, v203
	v_cvt_pk_bf16_f32 v202, v150, v151
	v_add_f32_e32 v160, v106, v160
	v_add_f32_e32 v161, v107, v161
; __device__ __forceinline__ unsigned cvt_pk_bf16(float lo, float hi) { unsigned r; asm volatile("v_cvt_pk_bf16_f32 %0, %1, %2" : "=v"(r) : "v"(lo), "v"(hi)); return r; }
; __device__ __forceinline__ float ebflo(unsigned w) { return __uint_as_float(w << 16); }
; __device__ __forceinline__ float ebfhi(unsigned w) { return __uint_as_float(w & 0xffff0000u); }
;     __device__ __forceinline__ void operator()(const f32x4 (&acc)[2][2][4][2], const Unit& u, int wr, int wc, int fr, int fq) const {
;         const int row0 = u.pm * BM + wr * 64 + fr, col0 = u.pn * BM + wc * 32 + 4 * fq;
; #pragma unroll
;         for (int ai = 0; ai < 2; ++ai)
; #pragma unroll
;             for (int m = 0; m < 4; ++m) { bf16_t* rowp = H + (size_t)(row0 + ai * HALF + m * 16) * 1024 + col0;
; #pragma unroll
;                 for (int bj = 0; bj < 2; ++bj)
; #pragma unroll
;                     for (int n = 0; n < 2; ++n) { u32x2* q = (u32x2*)(rowp + bj * HALF + n * 16); const u32x2 hv = *q; const f32x4 a = acc[ai][bj][m][n];
;                         u32x2 w; w.x = cvt_pk_bf16(ebflo(hv.x) + a[0], ebfhi(hv.x) + a[1]); w.y = cvt_pk_bf16(ebflo(hv.y) + a[2], ebfhi(hv.y) + a[3]); *q = w; } }
;     }
	s_nop 0
	v_cvt_pk_bf16_f32 v203, v160, v161
	s_nop 0
	global_store_dwordx2 v[148:149], v[202:203], off offset:256
	v_lshlrev_b32_e32 v150, 16, v204
	v_and_b32_e32 v151, 0xffff0000, v204
	v_add_f32_e32 v150, v100, v150
	v_add_f32_e32 v151, v101, v151
	v_lshlrev_b32_e32 v160, 16, v205
	v_and_b32_e32 v161, 0xffff0000, v205
	v_cvt_pk_bf16_f32 v204, v150, v151
	v_add_f32_e32 v160, v102, v160
	v_add_f32_e32 v161, v103, v161
	s_nop 0
	v_cvt_pk_bf16_f32 v205, v160, v161
	s_nop 0
	global_store_dwordx2 v[148:149], v[204:205], off offset:288
	s_mov_b64 s[10:11], 0x10000
	v_lshl_add_u64 v[148:149], v[146:147], 0, s[10:11]
	v_lshlrev_b32_e32 v150, 16, v206
	v_and_b32_e32 v151, 0xffff0000, v206
	v_add_f32_e32 v150, v96, v150
	v_add_f32_e32 v151, v97, v151
	v_lshlrev_b32_e32 v160, 16, v207
	v_and_b32_e32 v161, 0xffff0000, v207
	v_cvt_pk_bf16_f32 v206, v150, v151
	v_add_f32_e32 v160, v98, v160
	v_add_f32_e32 v161, v99, v161
	s_nop 0
	v_cvt_pk_bf16_f32 v207, v160, v161
	s_nop 0
	global_store_dwordx2 v[148:149], v[206:207], off
	v_lshlrev_b32_e32 v150, 16, v208
	v_and_b32_e32 v151, 0xffff0000, v208
	v_add_f32_e32 v150, v92, v150
	v_add_f32_e32 v151, v93, v151
	v_lshlrev_b32_e32 v160, 16, v209
	v_and_b32_e32 v161, 0xffff0000, v209
	v_cvt_pk_bf16_f32 v208, v150, v151
	v_add_f32_e32 v160, v94, v160
	v_add_f32_e32 v161, v95, v161
	s_nop 0
	v_cvt_pk_bf16_f32 v209, v160, v161
	s_nop 0
	global_store_dwordx2 v[148:149], v[208:209], off offset:32
	v_lshlrev_b32_e32 v150, 16, v210
	v_and_b32_e32 v151, 0xffff0000, v210
	v_add_f32_e32 v150, v88, v150
	v_add_f32_e32 v151, v89, v151
	v_lshlrev_b32_e32 v160, 16, v211
	v_and_b32_e32 v161, 0xffff0000, v211
	v_cvt_pk_bf16_f32 v210, v150, v151
	v_add_f32_e32 v160, v90, v160
	v_add_f32_e32 v161, v91, v161
	s_nop 0
	v_cvt_pk_bf16_f32 v211, v160, v161
	s_nop 0
	global_store_dwordx2 v[148:149], v[210:211], off offset:256
	v_lshlrev_b32_e32 v150, 16, v212
	v_and_b32_e32 v151, 0xffff0000, v212
	v_add_f32_e32 v150, v84, v150
	v_add_f32_e32 v151, v85, v151
	v_lshlrev_b32_e32 v160, 16, v213
	v_and_b32_e32 v161, 0xffff0000, v213
	v_cvt_pk_bf16_f32 v212, v150, v151
	v_add_f32_e32 v160, v86, v160
	v_add_f32_e32 v161, v87, v161
	s_nop 0
	v_cvt_pk_bf16_f32 v213, v160, v161
	s_nop 0
	global_store_dwordx2 v[148:149], v[212:213], off offset:288
	s_mov_b64 s[10:11], 0x18000
	v_lshl_add_u64 v[148:149], v[146:147], 0, s[10:11]
	v_lshlrev_b32_e32 v150, 16, v214
	v_and_b32_e32 v151, 0xffff0000, v214
	v_add_f32_e32 v150, v80, v150
	v_add_f32_e32 v151, v81, v151
	v_lshlrev_b32_e32 v160, 16, v215
	v_and_b32_e32 v161, 0xffff0000, v215
	v_cvt_pk_bf16_f32 v214, v150, v151
	v_add_f32_e32 v160, v82, v160
	v_add_f32_e32 v161, v83, v161
	s_nop 0
	v_cvt_pk_bf16_f32 v215, v160, v161
	s_nop 0
	global_store_dwordx2 v[148:149], v[214:215], off
	v_lshlrev_b32_e32 v150, 16, v216
	v_and_b32_e32 v151, 0xffff0000, v216
	v_add_f32_e32 v150, v76, v150
	v_add_f32_e32 v151, v77, v151
	v_lshlrev_b32_e32 v160, 16, v217
	v_and_b32_e32 v161, 0xffff0000, v217
	v_cvt_pk_bf16_f32 v216, v150, v151
	v_add_f32_e32 v160, v78, v160
	v_add_f32_e32 v161, v79, v161
	s_nop 0
	v_cvt_pk_bf16_f32 v217, v160, v161
	s_nop 0
	global_store_dwordx2 v[148:149], v[216:217], off offset:32
	v_lshlrev_b32_e32 v150, 16, v218
	v_and_b32_e32 v151, 0xffff0000, v218
	v_add_f32_e32 v150, v72, v150
	v_add_f32_e32 v151, v73, v151
	v_lshlrev_b32_e32 v160, 16, v219
	v_and_b32_e32 v161, 0xffff0000, v219
	v_cvt_pk_bf16_f32 v218, v150, v151
	v_add_f32_e32 v160, v74, v160
	v_add_f32_e32 v161, v75, v161
	s_nop 0
	v_cvt_pk_bf16_f32 v219, v160, v161
	s_nop 0
	global_store_dwordx2 v[148:149], v[218:219], off offset:256
	v_lshlrev_b32_e32 v150, 16, v220
	v_and_b32_e32 v151, 0xffff0000, v220
	v_add_f32_e32 v150, v68, v150
	v_add_f32_e32 v151, v69, v151
	v_lshlrev_b32_e32 v160, 16, v221
	v_and_b32_e32 v161, 0xffff0000, v221
	v_cvt_pk_bf16_f32 v220, v150, v151
	v_add_f32_e32 v160, v70, v160
	v_add_f32_e32 v161, v71, v161
	s_nop 0
	v_cvt_pk_bf16_f32 v221, v160, v161
	s_nop 0
	global_store_dwordx2 v[148:149], v[220:221], off offset:288
	s_mov_b64 s[10:11], 0x40000
	v_lshl_add_u64 v[148:149], v[146:147], 0, s[10:11]
	v_lshlrev_b32_e32 v150, 16, v222
	v_and_b32_e32 v151, 0xffff0000, v222
	v_add_f32_e32 v150, v64, v150
	v_add_f32_e32 v151, v65, v151
	v_lshlrev_b32_e32 v160, 16, v223
	v_and_b32_e32 v161, 0xffff0000, v223
	v_cvt_pk_bf16_f32 v222, v150, v151
	v_add_f32_e32 v160, v66, v160
	v_add_f32_e32 v161, v67, v161
	s_nop 0
	v_cvt_pk_bf16_f32 v223, v160, v161
	s_nop 0
	global_store_dwordx2 v[148:149], v[222:223], off
	v_lshlrev_b32_e32 v150, 16, v224
	v_and_b32_e32 v151, 0xffff0000, v224
	v_add_f32_e32 v150, v60, v150
	v_add_f32_e32 v151, v61, v151
	v_lshlrev_b32_e32 v160, 16, v225
	v_and_b32_e32 v161, 0xffff0000, v225
	v_cvt_pk_bf16_f32 v224, v150, v151
	v_add_f32_e32 v160, v62, v160
	v_add_f32_e32 v161, v63, v161
	s_nop 0
	v_cvt_pk_bf16_f32 v225, v160, v161
	s_nop 0
	global_store_dwordx2 v[148:149], v[224:225], off offset:32
	v_lshlrev_b32_e32 v150, 16, v226
	v_and_b32_e32 v151, 0xffff0000, v226
	v_add_f32_e32 v150, v56, v150
	v_add_f32_e32 v151, v57, v151
	v_lshlrev_b32_e32 v160, 16, v227
	v_and_b32_e32 v161, 0xffff0000, v227
	v_cvt_pk_bf16_f32 v226, v150, v151
	v_add_f32_e32 v160, v58, v160
	v_add_f32_e32 v161, v59, v161
	s_nop 0
	v_cvt_pk_bf16_f32 v227, v160, v161
	s_nop 0
	global_store_dwordx2 v[148:149], v[226:227], off offset:256
	v_lshlrev_b32_e32 v150, 16, v228
	v_and_b32_e32 v151, 0xffff0000, v228
	v_add_f32_e32 v150, v52, v150
	v_add_f32_e32 v151, v53, v151
; __device__ __forceinline__ unsigned cvt_pk_bf16(float lo, float hi) { unsigned r; asm volatile("v_cvt_pk_bf16_f32 %0, %1, %2" : "=v"(r) : "v"(lo), "v"(hi)); return r; }
; __device__ __forceinline__ float ebflo(unsigned w) { return __uint_as_float(w << 16); }
; __device__ __forceinline__ float ebfhi(unsigned w) { return __uint_as_float(w & 0xffff0000u); }
;     __device__ __forceinline__ void operator()(const f32x4 (&acc)[2][2][4][2], const Unit& u, int wr, int wc, int fr, int fq) const {
;         const int row0 = u.pm * BM + wr * 64 + fr, col0 = u.pn * BM + wc * 32 + 4 * fq;
; #pragma unroll
;         for (int ai = 0; ai < 2; ++ai)
; #pragma unroll
;             for (int m = 0; m < 4; ++m) { bf16_t* rowp = H + (size_t)(row0 + ai * HALF + m * 16) * 1024 + col0;
; #pragma unroll
;                 for (int bj = 0; bj < 2; ++bj)
; #pragma unroll
;                     for (int n = 0; n < 2; ++n) { u32x2* q = (u32x2*)(rowp + bj * HALF + n * 16); const u32x2 hv = *q; const f32x4 a = acc[ai][bj][m][n];
;                         u32x2 w; w.x = cvt_pk_bf16(ebflo(hv.x) + a[0], ebfhi(hv.x) + a[1]); w.y = cvt_pk_bf16(ebflo(hv.y) + a[2], ebfhi(hv.y) + a[3]); *q = w; } }
;     }
	v_lshlrev_b32_e32 v160, 16, v229
	v_and_b32_e32 v161, 0xffff0000, v229
	v_cvt_pk_bf16_f32 v228, v150, v151
	v_add_f32_e32 v160, v54, v160
	v_add_f32_e32 v161, v55, v161
	s_nop 0
	v_cvt_pk_bf16_f32 v229, v160, v161
	s_nop 0
	global_store_dwordx2 v[148:149], v[228:229], off offset:288
	s_mov_b64 s[10:11], 0x48000
	v_lshl_add_u64 v[148:149], v[146:147], 0, s[10:11]
	v_lshlrev_b32_e32 v150, 16, v230
	v_and_b32_e32 v151, 0xffff0000, v230
	v_add_f32_e32 v150, v48, v150
	v_add_f32_e32 v151, v49, v151
	v_lshlrev_b32_e32 v160, 16, v231
	v_and_b32_e32 v161, 0xffff0000, v231
	v_cvt_pk_bf16_f32 v230, v150, v151
	v_add_f32_e32 v160, v50, v160
	v_add_f32_e32 v161, v51, v161
	s_nop 0
	v_cvt_pk_bf16_f32 v231, v160, v161
	s_nop 0
	global_store_dwordx2 v[148:149], v[230:231], off
	v_lshlrev_b32_e32 v150, 16, v232
	v_and_b32_e32 v151, 0xffff0000, v232
	v_add_f32_e32 v150, v44, v150
	v_add_f32_e32 v151, v45, v151
	v_lshlrev_b32_e32 v160, 16, v233
	v_and_b32_e32 v161, 0xffff0000, v233
	v_cvt_pk_bf16_f32 v232, v150, v151
	v_add_f32_e32 v160, v46, v160
	v_add_f32_e32 v161, v47, v161
	s_nop 0
	v_cvt_pk_bf16_f32 v233, v160, v161
	s_nop 0
	global_store_dwordx2 v[148:149], v[232:233], off offset:32
	v_lshlrev_b32_e32 v150, 16, v234
	v_and_b32_e32 v151, 0xffff0000, v234
	v_add_f32_e32 v150, v40, v150
	v_add_f32_e32 v151, v41, v151
	v_lshlrev_b32_e32 v160, 16, v235
	v_and_b32_e32 v161, 0xffff0000, v235
	v_cvt_pk_bf16_f32 v234, v150, v151
	v_add_f32_e32 v160, v42, v160
	v_add_f32_e32 v161, v43, v161
	s_nop 0
	v_cvt_pk_bf16_f32 v235, v160, v161
	s_nop 0
	global_store_dwordx2 v[148:149], v[234:235], off offset:256
	v_lshlrev_b32_e32 v150, 16, v236
	v_and_b32_e32 v151, 0xffff0000, v236
	v_add_f32_e32 v150, v36, v150
	v_add_f32_e32 v151, v37, v151
	v_lshlrev_b32_e32 v160, 16, v237
	v_and_b32_e32 v161, 0xffff0000, v237
	v_cvt_pk_bf16_f32 v236, v150, v151
	v_add_f32_e32 v160, v38, v160
	v_add_f32_e32 v161, v39, v161
	s_nop 0
	v_cvt_pk_bf16_f32 v237, v160, v161
	s_nop 0
	global_store_dwordx2 v[148:149], v[236:237], off offset:288
	s_mov_b64 s[10:11], 0x50000
	v_lshl_add_u64 v[148:149], v[146:147], 0, s[10:11]
	v_lshlrev_b32_e32 v150, 16, v238
	v_and_b32_e32 v151, 0xffff0000, v238
	v_add_f32_e32 v150, v32, v150
	v_add_f32_e32 v151, v33, v151
	v_lshlrev_b32_e32 v160, 16, v239
	v_and_b32_e32 v161, 0xffff0000, v239
	v_cvt_pk_bf16_f32 v238, v150, v151
	v_add_f32_e32 v160, v34, v160
	v_add_f32_e32 v161, v35, v161
	s_nop 0
	v_cvt_pk_bf16_f32 v239, v160, v161
	s_nop 0
	global_store_dwordx2 v[148:149], v[238:239], off
	v_lshlrev_b32_e32 v150, 16, v240
	v_and_b32_e32 v151, 0xffff0000, v240
	v_add_f32_e32 v150, v28, v150
	v_add_f32_e32 v151, v29, v151
	v_lshlrev_b32_e32 v160, 16, v241
	v_and_b32_e32 v161, 0xffff0000, v241
	v_cvt_pk_bf16_f32 v240, v150, v151
	v_add_f32_e32 v160, v30, v160
	v_add_f32_e32 v161, v31, v161
	s_nop 0
	v_cvt_pk_bf16_f32 v241, v160, v161
	s_nop 0
	global_store_dwordx2 v[148:149], v[240:241], off offset:32
	v_lshlrev_b32_e32 v150, 16, v242
	v_and_b32_e32 v151, 0xffff0000, v242
	v_add_f32_e32 v150, v24, v150
	v_add_f32_e32 v151, v25, v151
	v_lshlrev_b32_e32 v160, 16, v243
	v_and_b32_e32 v161, 0xffff0000, v243
	v_cvt_pk_bf16_f32 v242, v150, v151
	v_add_f32_e32 v160, v26, v160
	v_add_f32_e32 v161, v27, v161
	s_nop 0
	v_cvt_pk_bf16_f32 v243, v160, v161
	s_nop 0
	global_store_dwordx2 v[148:149], v[242:243], off offset:256
	v_lshlrev_b32_e32 v150, 16, v244
	v_and_b32_e32 v151, 0xffff0000, v244
	v_add_f32_e32 v150, v20, v150
	v_add_f32_e32 v151, v21, v151
	v_lshlrev_b32_e32 v160, 16, v245
	v_and_b32_e32 v161, 0xffff0000, v245
	v_cvt_pk_bf16_f32 v244, v150, v151
	v_add_f32_e32 v160, v22, v160
	v_add_f32_e32 v161, v23, v161
	s_nop 0
	v_cvt_pk_bf16_f32 v245, v160, v161
	s_nop 0
	global_store_dwordx2 v[148:149], v[244:245], off offset:288
	s_mov_b64 s[10:11], 0x58000
	v_lshl_add_u64 v[148:149], v[146:147], 0, s[10:11]
	v_lshlrev_b32_e32 v150, 16, v152
	v_and_b32_e32 v151, 0xffff0000, v152
	v_add_f32_e32 v150, v16, v150
	v_add_f32_e32 v151, v17, v151
	v_lshlrev_b32_e32 v160, 16, v153
	v_and_b32_e32 v161, 0xffff0000, v153
	v_cvt_pk_bf16_f32 v152, v150, v151
	v_add_f32_e32 v160, v18, v160
	v_add_f32_e32 v161, v19, v161
	s_nop 0
	v_cvt_pk_bf16_f32 v153, v160, v161
	s_nop 0
	global_store_dwordx2 v[148:149], v[152:153], off
	v_lshlrev_b32_e32 v150, 16, v154
	v_and_b32_e32 v151, 0xffff0000, v154
	v_add_f32_e32 v150, v12, v150
	v_add_f32_e32 v151, v13, v151
	v_lshlrev_b32_e32 v160, 16, v155
	v_and_b32_e32 v161, 0xffff0000, v155
	v_cvt_pk_bf16_f32 v154, v150, v151
	v_add_f32_e32 v160, v14, v160
	v_add_f32_e32 v161, v15, v161
	s_nop 0
	v_cvt_pk_bf16_f32 v155, v160, v161
	s_nop 0
	global_store_dwordx2 v[148:149], v[154:155], off offset:32
	v_lshlrev_b32_e32 v150, 16, v156
	v_and_b32_e32 v151, 0xffff0000, v156
	v_add_f32_e32 v150, v8, v150
	v_add_f32_e32 v151, v9, v151
	v_lshlrev_b32_e32 v160, 16, v157
	v_and_b32_e32 v161, 0xffff0000, v157
	v_cvt_pk_bf16_f32 v156, v150, v151
	v_add_f32_e32 v160, v10, v160
	v_add_f32_e32 v161, v11, v161
	s_nop 0
	v_cvt_pk_bf16_f32 v157, v160, v161
	s_nop 0
	global_store_dwordx2 v[148:149], v[156:157], off offset:256
	v_lshlrev_b32_e32 v150, 16, v158
	v_and_b32_e32 v151, 0xffff0000, v158
	v_add_f32_e32 v150, v4, v150
	v_add_f32_e32 v151, v5, v151
	v_lshlrev_b32_e32 v160, 16, v159
	v_and_b32_e32 v161, 0xffff0000, v159
	v_cvt_pk_bf16_f32 v158, v150, v151
	v_add_f32_e32 v160, v6, v160
	v_add_f32_e32 v161, v7, v161
	s_nop 0
	v_cvt_pk_bf16_f32 v159, v160, v161
	s_nop 0
	global_store_dwordx2 v[148:149], v[158:159], off offset:288
